# MLP1 epilogue: lane transpose via ds_bpermute so adjacent lanes store contiguous 64B row segments (coalesced hid stores); plus earlier patches
# speedup vs baseline: 1.0176x; 1.0131x over previous
; DI float siluf(float x) { return x * __builtin_amdgcn_rcpf(1.f + __expf(-x)); }
; __device__ void mod_job(const Params& p, int job, char* smem) {
;     ...
;   for (int i = tid; i < 17 * 1024; i += NTHR) {
;     const int r = i >> 10, k = i & 1023;
;     const float v = (r < 16) ? p.c[r * 1024 + k] : p.c_ctx[k];
;     sc[i] = siluf(v);
;   }
.LBB0_44:
	v_mov_b32_e32 v82, v234
	s_movk_i32 s2, 0x4400
	s_nop 0
	v_cmp_gt_i32_e32 vcc, s2, v82
	s_and_saveexec_b64 s[2:3], vcc
	s_load_dwordx16 s[60:75], s[0:1], 0x0
	s_cbranch_execz .LBB0_47
	v_ashrrev_i32_e32 v83, 31, v82
	v_lshl_add_u32 v4, v82, 2, 0
	s_waitcnt lgkmcnt(0)
	v_mov_b32_e32 v174, v4
	global_load_dword v140, v174, s[62:63]
	global_load_dword v141, v174, s[62:63] offset:2048
	v_add_u32_e32 v174, 0x1000, v174
	global_load_dword v142, v174, s[62:63]
	global_load_dword v143, v174, s[62:63] offset:2048
	v_add_u32_e32 v174, 0x1000, v174
	global_load_dword v144, v174, s[62:63]
	global_load_dword v145, v174, s[62:63] offset:2048
	v_add_u32_e32 v174, 0x1000, v174
	global_load_dword v146, v174, s[62:63]
	global_load_dword v147, v174, s[62:63] offset:2048
	v_add_u32_e32 v174, 0x1000, v174
	global_load_dword v148, v174, s[62:63]
	global_load_dword v149, v174, s[62:63] offset:2048
	v_add_u32_e32 v174, 0x1000, v174
	global_load_dword v150, v174, s[62:63]
	global_load_dword v151, v174, s[62:63] offset:2048
	v_add_u32_e32 v174, 0x1000, v174
	global_load_dword v152, v174, s[62:63]
	global_load_dword v153, v174, s[62:63] offset:2048
	v_add_u32_e32 v174, 0x1000, v174
	global_load_dword v154, v174, s[62:63]
	global_load_dword v155, v174, s[62:63] offset:2048
	v_add_u32_e32 v174, 0x1000, v174
	global_load_dword v156, v174, s[62:63]
	global_load_dword v157, v174, s[62:63] offset:2048
	v_add_u32_e32 v174, 0x1000, v174
	global_load_dword v158, v174, s[62:63]
	global_load_dword v159, v174, s[62:63] offset:2048
	v_add_u32_e32 v174, 0x1000, v174
	global_load_dword v160, v174, s[62:63]
	global_load_dword v161, v174, s[62:63] offset:2048
	v_add_u32_e32 v174, 0x1000, v174
	global_load_dword v162, v174, s[62:63]
	global_load_dword v163, v174, s[62:63] offset:2048
	v_add_u32_e32 v174, 0x1000, v174
	global_load_dword v164, v174, s[62:63]
	global_load_dword v165, v174, s[62:63] offset:2048
	v_add_u32_e32 v174, 0x1000, v174
	global_load_dword v166, v174, s[62:63]
	global_load_dword v167, v174, s[62:63] offset:2048
	v_add_u32_e32 v174, 0x1000, v174
	global_load_dword v168, v174, s[62:63]
	global_load_dword v169, v174, s[62:63] offset:2048
	v_add_u32_e32 v174, 0x1000, v174
	global_load_dword v170, v174, s[62:63]
	global_load_dword v171, v174, s[62:63] offset:2048
	global_load_dword v176, v4, s[66:67]
	global_load_dword v177, v4, s[66:67] offset:2048
	v_add_u32_e32 v175, 0x10000, v4
	s_waitcnt vmcnt(32)
	v_mul_f32_e32 v5, 0xbfb8aa3b, v140
	v_mul_f32_e32 v6, 0xbfb8aa3b, v141
	v_exp_f32_e32 v5, v5
	v_exp_f32_e32 v6, v6
	s_nop 0
	v_add_f32_e32 v5, 1.0, v5
	v_add_f32_e32 v6, 1.0, v6
	v_rcp_f32_e32 v5, v5
	v_rcp_f32_e32 v6, v6
	s_nop 0
	v_mul_f32_e32 v5, v140, v5
	v_mul_f32_e32 v6, v141, v6
	ds_write_b32 v4, v5
	ds_write_b32 v4, v6 offset:2048
	s_waitcnt vmcnt(30)
	v_mul_f32_e32 v5, 0xbfb8aa3b, v142
	v_mul_f32_e32 v6, 0xbfb8aa3b, v143
	v_exp_f32_e32 v5, v5
	v_exp_f32_e32 v6, v6
	s_nop 0
	v_add_f32_e32 v5, 1.0, v5
	v_add_f32_e32 v6, 1.0, v6
	v_rcp_f32_e32 v5, v5
	v_rcp_f32_e32 v6, v6
	s_nop 0
	v_mul_f32_e32 v5, v142, v5
	v_mul_f32_e32 v6, v143, v6
	ds_write_b32 v4, v5 offset:4096
	ds_write_b32 v4, v6 offset:6144
	s_waitcnt vmcnt(28)
	v_mul_f32_e32 v5, 0xbfb8aa3b, v144
	v_mul_f32_e32 v6, 0xbfb8aa3b, v145
	v_exp_f32_e32 v5, v5
	v_exp_f32_e32 v6, v6
	s_nop 0
	v_add_f32_e32 v5, 1.0, v5
	v_add_f32_e32 v6, 1.0, v6
	v_rcp_f32_e32 v5, v5
	v_rcp_f32_e32 v6, v6
	s_nop 0
	v_mul_f32_e32 v5, v144, v5
	v_mul_f32_e32 v6, v145, v6
	ds_write_b32 v4, v5 offset:8192
	ds_write_b32 v4, v6 offset:10240
	s_waitcnt vmcnt(26)
	v_mul_f32_e32 v5, 0xbfb8aa3b, v146
	v_mul_f32_e32 v6, 0xbfb8aa3b, v147
	v_exp_f32_e32 v5, v5
	v_exp_f32_e32 v6, v6
	s_nop 0
	v_add_f32_e32 v5, 1.0, v5
	v_add_f32_e32 v6, 1.0, v6
	v_rcp_f32_e32 v5, v5
	v_rcp_f32_e32 v6, v6
	s_nop 0
	v_mul_f32_e32 v5, v146, v5
	v_mul_f32_e32 v6, v147, v6
	ds_write_b32 v4, v5 offset:12288
	ds_write_b32 v4, v6 offset:14336
	s_waitcnt vmcnt(24)
	v_mul_f32_e32 v5, 0xbfb8aa3b, v148
	v_mul_f32_e32 v6, 0xbfb8aa3b, v149
	v_exp_f32_e32 v5, v5
	v_exp_f32_e32 v6, v6
	s_nop 0
	v_add_f32_e32 v5, 1.0, v5
	v_add_f32_e32 v6, 1.0, v6
	v_rcp_f32_e32 v5, v5
	v_rcp_f32_e32 v6, v6
	s_nop 0
	v_mul_f32_e32 v5, v148, v5
	v_mul_f32_e32 v6, v149, v6
	ds_write_b32 v4, v5 offset:16384
	ds_write_b32 v4, v6 offset:18432
	s_waitcnt vmcnt(22)
; DI float siluf(float x) { return x * __builtin_amdgcn_rcpf(1.f + __expf(-x)); }
; __device__ void mod_job(const Params& p, int job, char* smem) {
;     ...
;   for (int i = tid; i < 17 * 1024; i += NTHR) {
;     const int r = i >> 10, k = i & 1023;
;     const float v = (r < 16) ? p.c[r * 1024 + k] : p.c_ctx[k];
;     sc[i] = siluf(v);
;   }
	v_mul_f32_e32 v5, 0xbfb8aa3b, v150
	v_mul_f32_e32 v6, 0xbfb8aa3b, v151
	v_exp_f32_e32 v5, v5
	v_exp_f32_e32 v6, v6
	s_nop 0
	v_add_f32_e32 v5, 1.0, v5
	v_add_f32_e32 v6, 1.0, v6
	v_rcp_f32_e32 v5, v5
	v_rcp_f32_e32 v6, v6
	s_nop 0
	v_mul_f32_e32 v5, v150, v5
	v_mul_f32_e32 v6, v151, v6
	ds_write_b32 v4, v5 offset:20480
	ds_write_b32 v4, v6 offset:22528
	s_waitcnt vmcnt(20)
	v_mul_f32_e32 v5, 0xbfb8aa3b, v152
	v_mul_f32_e32 v6, 0xbfb8aa3b, v153
	v_exp_f32_e32 v5, v5
	v_exp_f32_e32 v6, v6
	s_nop 0
	v_add_f32_e32 v5, 1.0, v5
	v_add_f32_e32 v6, 1.0, v6
	v_rcp_f32_e32 v5, v5
	v_rcp_f32_e32 v6, v6
	s_nop 0
	v_mul_f32_e32 v5, v152, v5
	v_mul_f32_e32 v6, v153, v6
	ds_write_b32 v4, v5 offset:24576
	ds_write_b32 v4, v6 offset:26624
	s_waitcnt vmcnt(18)
	v_mul_f32_e32 v5, 0xbfb8aa3b, v154
	v_mul_f32_e32 v6, 0xbfb8aa3b, v155
	v_exp_f32_e32 v5, v5
	v_exp_f32_e32 v6, v6
	s_nop 0
	v_add_f32_e32 v5, 1.0, v5
	v_add_f32_e32 v6, 1.0, v6
	v_rcp_f32_e32 v5, v5
	v_rcp_f32_e32 v6, v6
	s_nop 0
	v_mul_f32_e32 v5, v154, v5
	v_mul_f32_e32 v6, v155, v6
	ds_write_b32 v4, v5 offset:28672
	ds_write_b32 v4, v6 offset:30720
	s_waitcnt vmcnt(16)
	v_mul_f32_e32 v5, 0xbfb8aa3b, v156
	v_mul_f32_e32 v6, 0xbfb8aa3b, v157
	v_exp_f32_e32 v5, v5
	v_exp_f32_e32 v6, v6
	s_nop 0
	v_add_f32_e32 v5, 1.0, v5
	v_add_f32_e32 v6, 1.0, v6
	v_rcp_f32_e32 v5, v5
	v_rcp_f32_e32 v6, v6
	s_nop 0
	v_mul_f32_e32 v5, v156, v5
	v_mul_f32_e32 v6, v157, v6
	ds_write_b32 v4, v5 offset:32768
	ds_write_b32 v4, v6 offset:34816
	s_waitcnt vmcnt(14)
	v_mul_f32_e32 v5, 0xbfb8aa3b, v158
	v_mul_f32_e32 v6, 0xbfb8aa3b, v159
	v_exp_f32_e32 v5, v5
	v_exp_f32_e32 v6, v6
	s_nop 0
	v_add_f32_e32 v5, 1.0, v5
	v_add_f32_e32 v6, 1.0, v6
	v_rcp_f32_e32 v5, v5
	v_rcp_f32_e32 v6, v6
	s_nop 0
	v_mul_f32_e32 v5, v158, v5
	v_mul_f32_e32 v6, v159, v6
	ds_write_b32 v4, v5 offset:36864
	ds_write_b32 v4, v6 offset:38912
	s_waitcnt vmcnt(12)
	v_mul_f32_e32 v5, 0xbfb8aa3b, v160
	v_mul_f32_e32 v6, 0xbfb8aa3b, v161
	v_exp_f32_e32 v5, v5
	v_exp_f32_e32 v6, v6
	s_nop 0
	v_add_f32_e32 v5, 1.0, v5
	v_add_f32_e32 v6, 1.0, v6
	v_rcp_f32_e32 v5, v5
	v_rcp_f32_e32 v6, v6
	s_nop 0
	v_mul_f32_e32 v5, v160, v5
	v_mul_f32_e32 v6, v161, v6
	ds_write_b32 v4, v5 offset:40960
	ds_write_b32 v4, v6 offset:43008
	s_waitcnt vmcnt(10)
	v_mul_f32_e32 v5, 0xbfb8aa3b, v162
	v_mul_f32_e32 v6, 0xbfb8aa3b, v163
	v_exp_f32_e32 v5, v5
	v_exp_f32_e32 v6, v6
	s_nop 0
	v_add_f32_e32 v5, 1.0, v5
	v_add_f32_e32 v6, 1.0, v6
	v_rcp_f32_e32 v5, v5
	v_rcp_f32_e32 v6, v6
	s_nop 0
	v_mul_f32_e32 v5, v162, v5
	v_mul_f32_e32 v6, v163, v6
	ds_write_b32 v4, v5 offset:45056
	ds_write_b32 v4, v6 offset:47104
	s_waitcnt vmcnt(8)
	v_mul_f32_e32 v5, 0xbfb8aa3b, v164
	v_mul_f32_e32 v6, 0xbfb8aa3b, v165
	v_exp_f32_e32 v5, v5
	v_exp_f32_e32 v6, v6
	s_nop 0
	v_add_f32_e32 v5, 1.0, v5
	v_add_f32_e32 v6, 1.0, v6
	v_rcp_f32_e32 v5, v5
	v_rcp_f32_e32 v6, v6
	s_nop 0
	v_mul_f32_e32 v5, v164, v5
	v_mul_f32_e32 v6, v165, v6
	ds_write_b32 v4, v5 offset:49152
	ds_write_b32 v4, v6 offset:51200
	s_waitcnt vmcnt(6)
	v_mul_f32_e32 v5, 0xbfb8aa3b, v166
	v_mul_f32_e32 v6, 0xbfb8aa3b, v167
	v_exp_f32_e32 v5, v5
	v_exp_f32_e32 v6, v6
	s_nop 0
	v_add_f32_e32 v5, 1.0, v5
	v_add_f32_e32 v6, 1.0, v6
	v_rcp_f32_e32 v5, v5
	v_rcp_f32_e32 v6, v6
	s_nop 0
	v_mul_f32_e32 v5, v166, v5
	v_mul_f32_e32 v6, v167, v6
	ds_write_b32 v4, v5 offset:53248
	ds_write_b32 v4, v6 offset:55296
	s_waitcnt vmcnt(4)
	v_mul_f32_e32 v5, 0xbfb8aa3b, v168
	v_mul_f32_e32 v6, 0xbfb8aa3b, v169
	v_exp_f32_e32 v5, v5
	v_exp_f32_e32 v6, v6
	s_nop 0
	v_add_f32_e32 v5, 1.0, v5
	v_add_f32_e32 v6, 1.0, v6
	v_rcp_f32_e32 v5, v5
	v_rcp_f32_e32 v6, v6
	s_nop 0
	v_mul_f32_e32 v5, v168, v5
	v_mul_f32_e32 v6, v169, v6
	ds_write_b32 v4, v5 offset:57344
	ds_write_b32 v4, v6 offset:59392
	s_waitcnt vmcnt(2)
	v_mul_f32_e32 v5, 0xbfb8aa3b, v170
	v_mul_f32_e32 v6, 0xbfb8aa3b, v171
	v_exp_f32_e32 v5, v5
	v_exp_f32_e32 v6, v6
	s_nop 0
	v_add_f32_e32 v5, 1.0, v5
	v_add_f32_e32 v6, 1.0, v6
	v_rcp_f32_e32 v5, v5
	v_rcp_f32_e32 v6, v6
	s_nop 0
	v_mul_f32_e32 v5, v170, v5
	v_mul_f32_e32 v6, v171, v6
	ds_write_b32 v4, v5 offset:61440
	ds_write_b32 v4, v6 offset:63488
	s_waitcnt vmcnt(0)
	v_mul_f32_e32 v5, 0xbfb8aa3b, v176
	v_mul_f32_e32 v6, 0xbfb8aa3b, v177
	v_exp_f32_e32 v5, v5
	v_exp_f32_e32 v6, v6
	s_nop 0
	v_add_f32_e32 v5, 1.0, v5
	v_add_f32_e32 v6, 1.0, v6
	v_rcp_f32_e32 v5, v5
	v_rcp_f32_e32 v6, v6
	s_nop 0
	v_mul_f32_e32 v5, v176, v5
	v_mul_f32_e32 v6, v177, v6
	ds_write_b32 v175, v5
	ds_write_b32 v175, v6 offset:2048

; template <int NB>
; DI void softmax_pv(f32x16 (&s)[2], float& mrun, float& lsum, f32x16 (&O)[2], unsigned vaddr) {
;     ...
;   float mx = -1e30f;
; #pragma unroll
;   for (int kb = 0; kb < NB; ++kb)
; #pragma unroll
;     for (int e = 0; e < 16; ++e) mx = fmaxf(mx, s[kb][e]);
;   mx = xmax32(mx);
;   constexpr float THR = 8.f;
;   float alpha = 1.f;
;   if (__builtin_amdgcn_ballot_w64(mx - mrun > THR) != 0ull) {
;     const float mnew = fmaxf(mrun, mx);
;     alpha = __builtin_amdgcn_exp2f((mrun - mnew) * L2E);
;     mrun = mnew;
; #pragma unroll
;     for (int e = 0; e < 16; ++e) { O[0][e] *= alpha; O[1][e] *= alpha; }
; template <int kind>
; __device__ void attn_job(const Params& p, int layer, int idx, char* smem) {
;     ...
;     u16* Kb = Ks + (i & 1) * 64 * KS_STRIDE;
;     u16* Vb = Vt + (i & 1) * 64 * KS_STRIDE;
;     *(u32x4*)(Kb + lkey * KS_STRIDE + lc * 8) = kreg;
;     *(u32x4*)(Vb + lkey * KS_STRIDE + lc * 8) = vreg;
;     lds_barrier();
;     if (i + 1 < ntiles) {
;       const size_t ro = (size_t)(tile_row0(i + 1) + lkey) * ZW;
;       kreg = *(const u32x4*)(Z + ro + kcol + lc * 8);
;       vreg = *(const u32x4*)(Z + ro + vcol + lc * 8);
;     }
;     if (kind == 1 && i >= 4) {
;       const int kr = R0 + i - 4;
;       if (kr >= r0A && kr < r0A + 9) {
;         f32x16 s[2];
; #pragma unroll
;         for (int st = 0; st < 4; ++st) s[0] = mfma32(ld_frag16(Kb + (k0 + tq) * KS_STRIDE + 16 * st + 8 * hh), qf[st], st == 0 ? zero16 : s[0]);
;         const bool rowvalid = (kr >= r0l) && (kr < r0l + 8);
;         const unsigned m = rowvalid ? colmask : 0u;
;         const float* brow = rpbs + (kr - qrow_l + 7) * 32 + dcbase;
; #pragma unroll
;         for (int e = 0; e < 16; ++e) {
;           const float bias = brow[(e & 3) + 8 * (e >> 2)];
;           s[0][e] = ((m >> e) & 1u) ? s[0][e] + bias : -1e30f;
;         }
;         softmax_pv<1>(s, mrun, lsum, O, (unsigned)(size_t)Vb + vlane_off + (unsigned)(k0 * KS_STRIDE * 2));
;       }
;     } else {
;       f32x16 s[2];
;       __builtin_amdgcn_s_setprio(1);
; #pragma unroll
;       for (int kb = 0; kb < 2; ++kb) {
; #pragma unroll
;         for (int st = 0; st < 4; ++st) s[kb] = mfma32(ld_frag16(Kb + (kb * 32 + tq) * KS_STRIDE + 16 * st + 8 * hh), qf[st], st == 0 ? zero16 : s[kb]);
;       }
;       __builtin_amdgcn_s_setprio(0);
;       softmax_pv<2>(s, mrun, lsum, O, (unsigned)(size_t)Vb + vlane_off);
.LBB0_520:
	s_and_b32 s3, s6, 64
	s_mulk_i32 s3, 0x90
	s_add_i32 s10, s3, 0
	s_add_i32 s11, s10, 0x4800
	s_cmp_lt_u32 s7, 3
	s_cselect_b32 s3, 0x8000, s26
	s_cselect_b32 s8, s5, s4
	v_lshlrev_b32_e32 v0, 1, v142
	s_add_i32 s3, s8, s3
	v_add3_u32 v50, s10, v148, v0
	s_add_i32 s3, s3, s6
	s_waitcnt vmcnt(1)
	ds_write_b128 v50, v[98:101]
	s_waitcnt vmcnt(0)
	ds_write_b128 v50, v[102:105] offset:18432
	v_add_u32_e32 v52, s3, v147
	v_mov_b64_e32 v[50:51], s[80:81]
	v_mad_i64_i32 v[50:51], s[8:9], v52, s79, v[50:51]
	v_readlane_b32 s8, v254, 34
	v_readlane_b32 s9, v254, 35
	s_mov_b32 s3, s9
	s_waitcnt lgkmcnt(0)
	s_barrier
	v_lshl_add_u64 v[52:53], v[50:51], 0, s[8:9]
	v_lshl_add_u64 v[52:53], v[52:53], 0, v[0:1]
	v_lshl_add_u64 v[50:51], v[50:51], 0, s[2:3]
	v_lshl_add_u64 v[50:51], v[50:51], 0, v[0:1]
	global_load_dwordx4 v[98:101], v[52:53], off
	global_load_dwordx4 v[102:105], v[50:51], off
	s_setprio 1
	v_add3_u32 v110, s10, v140, v143
	v_add_u32_e32 v144, s11, v141
	ds_read_b128 v[178:181], v110
	ds_read_b128 v[182:185], v110 offset:32
	ds_read_b128 v[186:189], v110 offset:64
	ds_read_b128 v[190:193], v110 offset:96
	ds_read_b128 v[194:197], v110 offset:4608
	ds_read_b128 v[198:201], v110 offset:4640
	ds_read_b128 v[202:205], v110 offset:4672
	ds_read_b128 v[206:209], v110 offset:4704
	ds_read_b64_tr_b16 v[134:135], v144 offset:0
	ds_read_b64_tr_b16 v[136:137], v144 offset:1152
	ds_read_b64_tr_b16 v[130:131], v144 offset:64
	ds_read_b64_tr_b16 v[132:133], v144 offset:1216
	s_waitcnt lgkmcnt(11)
	v_mfma_f32_32x32x16_bf16 v[66:81], v[178:181], v[94:97], v[34:49]
	ds_read_b64_tr_b16 v[126:127], v144 offset:2304
	s_waitcnt lgkmcnt(11)
	v_mfma_f32_32x32x16_bf16 v[66:81], v[182:185], v[90:93], v[66:81]
	ds_read_b64_tr_b16 v[128:129], v144 offset:3456
	s_waitcnt lgkmcnt(11)
	v_mfma_f32_32x32x16_bf16 v[66:81], v[186:189], v[86:89], v[66:81]
	ds_read_b64_tr_b16 v[122:123], v144 offset:2368
	s_waitcnt lgkmcnt(11)
	v_mfma_f32_32x32x16_bf16 v[66:81], v[190:193], v[82:85], v[66:81]
	ds_read_b64_tr_b16 v[124:125], v144 offset:3520
	s_waitcnt lgkmcnt(11)
	v_mfma_f32_32x32x16_bf16 v[50:65], v[194:197], v[94:97], v[34:49]
	ds_read_b64_tr_b16 v[118:119], v144 offset:4608
	s_waitcnt lgkmcnt(11)
	v_mfma_f32_32x32x16_bf16 v[50:65], v[198:201], v[90:93], v[50:65]
	ds_read_b64_tr_b16 v[120:121], v144 offset:5760
	s_waitcnt lgkmcnt(11)
	v_mfma_f32_32x32x16_bf16 v[50:65], v[202:205], v[86:89], v[50:65]
	ds_read_b64_tr_b16 v[114:115], v144 offset:4672
	s_waitcnt lgkmcnt(11)
	v_mfma_f32_32x32x16_bf16 v[50:65], v[206:209], v[82:85], v[50:65]
	ds_read_b64_tr_b16 v[116:117], v144 offset:5824
	ds_read_b64_tr_b16 v[110:111], v144 offset:6912
	ds_read_b64_tr_b16 v[112:113], v144 offset:8064
	ds_read_b64_tr_b16 v[106:107], v144 offset:6976
	ds_read_b64_tr_b16 v[108:109], v144 offset:8128
	s_setprio 0
	v_max3_f32 v144, v66, s24, v67
	v_max3_f32 v144, v144, v68, v69
	v_max3_f32 v144, v144, v70, v71
	v_max3_f32 v144, v144, v72, v73
	v_max3_f32 v144, v144, v74, v75
	v_max3_f32 v144, v144, v76, v77
	v_max3_f32 v144, v144, v78, v79
	v_max3_f32 v144, v144, v80, v81
	s_nop 1
	v_max3_f32 v144, v144, v50, v51
	v_max3_f32 v144, v144, v52, v53
	v_max3_f32 v144, v144, v54, v55
	v_max3_f32 v144, v144, v56, v57
	v_max3_f32 v144, v144, v58, v59
	v_max3_f32 v144, v144, v60, v61
	v_max3_f32 v144, v144, v62, v63
	v_max3_f32 v144, v144, v64, v65
	v_mov_b32_e32 v146, v144
	s_nop 1
	v_permlane32_swap_b32_e32 v144, v146
	v_max_f32_e32 v146, v146, v146
	v_max_f32_e32 v144, v144, v144
	v_max_f32_e32 v144, v144, v146
	v_sub_f32_e32 v146, v144, v145
	v_cmp_lt_f32_e32 vcc, s25, v146
	s_cbranch_vccz .LBB0_522
	v_max_f32_e32 v144, v144, v144
	v_max_f32_e32 v146, v145, v145
	v_max_f32_e32 v144, v146, v144
	v_sub_f32_e32 v145, v145, v144
	v_mul_f32_e32 v145, 0x3fb8aa3b, v145
	v_exp_f32_e32 v146, v145
	v_mov_b32_e32 v145, v144
	v_pk_mul_f32 v[32:33], v[32:33], v[146:147] op_sel_hi:[1,0]
	v_pk_mul_f32 v[30:31], v[30:31], v[146:147] op_sel_hi:[1,0]
	v_pk_mul_f32 v[28:29], v[28:29], v[146:147] op_sel_hi:[1,0]
	v_pk_mul_f32 v[26:27], v[26:27], v[146:147] op_sel_hi:[1,0]
	v_pk_mul_f32 v[24:25], v[24:25], v[146:147] op_sel_hi:[1,0]
	v_pk_mul_f32 v[22:23], v[22:23], v[146:147] op_sel_hi:[1,0]
	v_pk_mul_f32 v[20:21], v[20:21], v[146:147] op_sel_hi:[1,0]
	v_pk_mul_f32 v[18:19], v[18:19], v[146:147] op_sel_hi:[1,0]
	v_pk_mul_f32 v[16:17], v[16:17], v[146:147] op_sel_hi:[1,0]
	v_pk_mul_f32 v[14:15], v[14:15], v[146:147] op_sel_hi:[1,0]
	v_pk_mul_f32 v[12:13], v[12:13], v[146:147] op_sel_hi:[1,0]
	v_pk_mul_f32 v[10:11], v[10:11], v[146:147] op_sel_hi:[1,0]
	v_pk_mul_f32 v[8:9], v[8:9], v[146:147] op_sel_hi:[1,0]
	v_pk_mul_f32 v[6:7], v[6:7], v[146:147] op_sel_hi:[1,0]
	v_pk_mul_f32 v[4:5], v[4:5], v[146:147] op_sel_hi:[1,0]
	v_pk_mul_f32 v[2:3], v[2:3], v[146:147] op_sel_hi:[1,0]
	s_branch .LBB0_523

; DI f32x16 mfma32(bf16x8 a, bf16x8 b, f32x16 c) { return __builtin_amdgcn_mfma_f32_32x32x16_bf16(a, b, c, 0, 0, 0); }
; template <int NB>
; DI void softmax_pv(f32x16 (&s)[2], float& mrun, float& lsum, f32x16 (&O)[2], unsigned vaddr) {
;     ...
;   typedef float f32x2 __attribute__((ext_vector_type(2)));
;   const float mb = mrun * L2E;
;   f32x2 ps2 = {0.f, 0.f};
;   const f32x2 l2e2 = {L2E, L2E}, mb2 = {mb, mb};
;   if (NB == 2) {
; #pragma unroll
;     for (int kb = 0; kb < 2; ++kb) {
; #pragma unroll
;       for (int e = 0; e < 16; e += 2) {
;         f32x2 t = {s[kb][e], s[kb][e + 1]};
;         t = t * l2e2 - mb2;
;         f32x2 pv;
;         pv[0] = __builtin_amdgcn_exp2f(t[0]);
;         pv[1] = __builtin_amdgcn_exp2f(t[1]);
;         s[kb][e] = pv[0];
;         s[kb][e + 1] = pv[1];
;         ps2 += pv;
;       }
;       u32x4 pp[2];
; #pragma unroll
;       for (int st = 0; st < 2; ++st)
; #pragma unroll
;         for (int j = 0; j < 4; ++j) pp[st][j] = pk_bf16(s[kb][8 * st + 2 * j], s[kb][8 * st + 2 * j + 1]);
;       __builtin_amdgcn_sched_barrier(0);
;       __builtin_amdgcn_s_setprio(1);
; #pragma unroll
;       for (int st = 0; st < 2; ++st) {
;         const bf16x8 pf = as_bf16x8(pp[st]);
; #pragma unroll
;         for (int db = 0; db < 2; ++db) {
;           const int ix = ((kb * 2 + st) * 2 + db) * 2;
;           u32x4 av;
;           av[0] = vf[ix][0]; av[1] = vf[ix][1]; av[2] = vf[ix + 1][0]; av[3] = vf[ix + 1][1];
;           O[db] = mfma32(as_bf16x8(av), pf, O[db]);
;         }
;       }
;       __builtin_amdgcn_s_setprio(0);
;       __builtin_amdgcn_sched_barrier(0);
;     }
.LBB0_523:
	v_mul_f32_e32 v144, 0x3fb8aa3b, v145
	v_pk_fma_f32 v[66:67], v[66:67], s[28:29], v[144:145] op_sel_hi:[1,0,0] neg_lo:[0,0,1] neg_hi:[0,0,1]
	s_add_i32 s7, s7, 1
	v_exp_f32_e32 v150, v66
	v_exp_f32_e32 v151, v67
	v_pk_fma_f32 v[66:67], v[68:69], s[28:29], v[144:145] op_sel_hi:[1,0,0] neg_lo:[0,0,1] neg_hi:[0,0,1]
	s_nop 0
	v_exp_f32_e32 v152, v66
	v_exp_f32_e32 v153, v67
	v_pk_fma_f32 v[66:67], v[70:71], s[28:29], v[144:145] op_sel_hi:[1,0,0] neg_lo:[0,0,1] neg_hi:[0,0,1]
	s_nop 0
	v_exp_f32_e32 v154, v66
	v_exp_f32_e32 v155, v67
	v_pk_fma_f32 v[66:67], v[72:73], s[28:29], v[144:145] op_sel_hi:[1,0,0] neg_lo:[0,0,1] neg_hi:[0,0,1]
	v_cvt_pk_bf16_f32 v68, v154, v155
	v_exp_f32_e32 v156, v66
	v_exp_f32_e32 v157, v67
	v_pk_fma_f32 v[66:67], v[74:75], s[28:29], v[144:145] op_sel_hi:[1,0,0] neg_lo:[0,0,1] neg_hi:[0,0,1]
	v_cvt_pk_bf16_f32 v69, v156, v157
	v_exp_f32_e32 v74, v66
	v_exp_f32_e32 v75, v67
	v_pk_fma_f32 v[66:67], v[76:77], s[28:29], v[144:145] op_sel_hi:[1,0,0] neg_lo:[0,0,1] neg_hi:[0,0,1]
	v_cvt_pk_bf16_f32 v70, v74, v75
	v_exp_f32_e32 v76, v66
	v_exp_f32_e32 v77, v67
	v_pk_fma_f32 v[66:67], v[78:79], s[28:29], v[144:145] op_sel_hi:[1,0,0] neg_lo:[0,0,1] neg_hi:[0,0,1]
	v_cvt_pk_bf16_f32 v71, v76, v77
	v_exp_f32_e32 v78, v66
	v_exp_f32_e32 v79, v67
	v_pk_fma_f32 v[66:67], v[80:81], s[28:29], v[144:145] op_sel_hi:[1,0,0] neg_lo:[0,0,1] neg_hi:[0,0,1]
	v_cvt_pk_bf16_f32 v72, v78, v79
	v_exp_f32_e32 v80, v66
	v_exp_f32_e32 v81, v67
	v_cvt_pk_bf16_f32 v66, v150, v151
	v_cvt_pk_bf16_f32 v67, v152, v153
	v_cvt_pk_bf16_f32 v73, v80, v81
	s_waitcnt lgkmcnt(0)
	s_setprio 1
	v_mfma_f32_32x32x16_bf16 v[18:33], v[134:137], v[66:69], v[18:33]
	v_mfma_f32_32x32x16_bf16 v[2:17], v[130:133], v[66:69], v[2:17]
	v_add_f32_e64 v66, v150, 0
	v_add_f32_e64 v67, v151, 0
	v_add_f32_e64 v66, v152, v66
	v_add_f32_e64 v67, v153, v67
	v_add_f32_e64 v66, v154, v66
	v_add_f32_e64 v67, v155, v67
	v_pk_add_f32 v[66:67], v[156:157], v[66:67]
	v_mfma_f32_32x32x16_bf16 v[18:33], v[126:129], v[70:73], v[18:33]
	v_add_f32_e64 v66, v74, v66
	v_add_f32_e64 v67, v75, v67
	v_add_f32_e64 v66, v76, v66
	v_add_f32_e64 v67, v77, v67
	v_add_f32_e64 v66, v78, v66
	v_add_f32_e64 v67, v79, v67
	v_pk_add_f32 v[66:67], v[80:81], v[66:67]
	v_mfma_f32_32x32x16_bf16 v[2:17], v[122:125], v[70:73], v[2:17]
	s_setprio 0
	v_fma_f32 v50, v50, s28, -v144
	v_fma_f32 v51, v51, s28, -v144
	v_exp_f32_e32 v68, v50
	v_exp_f32_e32 v69, v51
	v_pk_fma_f32 v[50:51], v[52:53], s[28:29], v[144:145] op_sel_hi:[1,0,0] neg_lo:[0,0,1] neg_hi:[0,0,1]
	s_nop 0
	v_exp_f32_e32 v70, v50
	v_exp_f32_e32 v71, v51
	v_pk_fma_f32 v[50:51], v[54:55], s[28:29], v[144:145] op_sel_hi:[1,0,0] neg_lo:[0,0,1] neg_hi:[0,0,1]
	s_nop 0
	v_exp_f32_e32 v72, v50
	v_exp_f32_e32 v73, v51
	v_pk_fma_f32 v[50:51], v[56:57], s[28:29], v[144:145] op_sel_hi:[1,0,0] neg_lo:[0,0,1] neg_hi:[0,0,1]
	v_cvt_pk_bf16_f32 v52, v72, v73
	v_exp_f32_e32 v74, v50
	v_exp_f32_e32 v75, v51
	v_pk_fma_f32 v[50:51], v[58:59], s[28:29], v[144:145] op_sel_hi:[1,0,0] neg_lo:[0,0,1] neg_hi:[0,0,1]
	v_cvt_pk_bf16_f32 v53, v74, v75
	v_exp_f32_e32 v58, v50
	v_exp_f32_e32 v59, v51
	v_pk_fma_f32 v[50:51], v[60:61], s[28:29], v[144:145] op_sel_hi:[1,0,0] neg_lo:[0,0,1] neg_hi:[0,0,1]
	v_cvt_pk_bf16_f32 v54, v58, v59
	v_exp_f32_e32 v60, v50
	v_exp_f32_e32 v61, v51
	v_pk_fma_f32 v[50:51], v[62:63], s[28:29], v[144:145] op_sel_hi:[1,0,0] neg_lo:[0,0,1] neg_hi:[0,0,1]
	v_cvt_pk_bf16_f32 v55, v60, v61
	v_exp_f32_e32 v62, v50
	v_exp_f32_e32 v63, v51
	v_pk_fma_f32 v[50:51], v[64:65], s[28:29], v[144:145] op_sel_hi:[1,0,0] neg_lo:[0,0,1] neg_hi:[0,0,1]
	v_cvt_pk_bf16_f32 v56, v62, v63
	v_exp_f32_e32 v64, v50
	v_exp_f32_e32 v65, v51
	v_cvt_pk_bf16_f32 v50, v68, v69
	v_cvt_pk_bf16_f32 v51, v70, v71
	v_cvt_pk_bf16_f32 v57, v64, v65
	s_setprio 1
	v_mfma_f32_32x32x16_bf16 v[18:33], v[118:121], v[50:53], v[18:33]
	v_mfma_f32_32x32x16_bf16 v[2:17], v[114:117], v[50:53], v[2:17]
	v_add_f32_e64 v50, v68, v66
	v_add_f32_e64 v51, v69, v67
	v_add_f32_e64 v50, v70, v50
	v_add_f32_e64 v51, v71, v51
	v_add_f32_e64 v50, v72, v50
	v_add_f32_e64 v51, v73, v51
	v_pk_add_f32 v[50:51], v[74:75], v[50:51]
	v_mfma_f32_32x32x16_bf16 v[18:33], v[110:113], v[54:57], v[18:33]
	v_add_f32_e64 v50, v58, v50
	v_add_f32_e64 v51, v59, v51
	v_add_f32_e64 v50, v60, v50
	v_add_f32_e64 v51, v61, v51
	v_add_f32_e64 v50, v62, v50
	v_add_f32_e64 v51, v63, v51
	v_pk_add_f32 v[50:51], v[64:65], v[50:51]
	v_mfma_f32_32x32x16_bf16 v[2:17], v[106:109], v[54:57], v[2:17]
	s_setprio 0
	v_add_f32_e32 v106, v50, v51
	s_add_i32 s6, s6, 64
	s_cmp_eq_u32 s7, 35
	v_fmac_f32_e32 v106, v149, v146
	s_cbranch_scc1 .LBB0_525
	v_mov_b32_e32 v149, v106
	s_branch .LBB0_520

; template <int EPI>
; DI void gemm_epilogue(const Params& p, int layer, f32x4 (&acc)[2][2][4][2], int brow, int bcol, int pn, int wr, int wc,
;                       int fr, int fq, char* smem, int ksplit = -1) {
;     ...
; #pragma unroll
;     for (int ai = 0; ai < 2; ++ai)
; #pragma unroll
;       for (int m = 0; m < 4; ++m) {
;         __builtin_amdgcn_sched_barrier(0);
;         const int row = brow + ai * 128 + wr * 64 + m * 16 + fr;
;         const float rs = __builtin_amdgcn_rsqf(rsv[ai][m] * (1.f / DM) + EPSN);
; #pragma unroll
;         for (int bj = 0; bj < 2; ++bj) {
;           u32x4 o;
; #pragma unroll
;           for (int n = 0; n < 2; ++n) {
;             f32x4 v = acc[ai][bj][m][n] * rs + bv[bj][n];
; #pragma unroll
;             for (int j = 0; j < 4; ++j) {
;               float r = fmaxf(v[j], 0.f);
;               v[j] = r * r;
;             }
;             o[2 * n] = pk_bf16(v[0], v[1]);
;             o[2 * n + 1] = pk_bf16(v[2], v[3]);
;           }
;           *(u32x4*)(p.hid + (size_t)row * HID + colb + bj * 128) = o;
;         }
;       }
.LBB0_997:
	s_lshl_b32 s20, s18, 8
	s_min_i32 s13, s20, 0x8000
	v_mov_b32_e32 v130, v234
	s_ashr_i32 s13, s13, 11
	v_readlane_b32 s18, v255, 10
	s_add_i32 s22, s13, s18
	s_lshl_b32 s11, s47, 8
	v_and_b32_e32 v156, 15, v130
	s_ashr_i32 s23, s22, 31
	v_lshrrev_b32_e32 v130, 1, v130
	s_lshl_b64 s[22:23], s[22:23], 14
	v_and_or_b32 v130, v130, 24, s11
	s_add_u32 s22, s90, s22
	v_or_b32_e32 v162, s39, v130
	s_addc_u32 s23, s91, s23
	v_ashrrev_i32_e32 v163, 31, v162
	s_ashr_i32 s21, s20, 31
	v_lshl_add_u64 v[134:135], v[162:163], 2, s[22:23]
	s_lshl_b64 s[22:23], s[20:21], 2
	s_add_u32 s22, s7, s22
	s_addc_u32 s23, s44, s23
	v_lshlrev_b32_e32 v157, 2, v156
	global_load_dwordx4 v[138:141], v[134:135], off offset:16
	global_load_dwordx4 v[142:145], v[134:135], off
	global_load_dwordx4 v[130:133], v[134:135], off offset:528
	s_nop 0
	global_load_dwordx4 v[134:137], v[134:135], off offset:512
	s_nop 0
	global_load_dword v164, v157, s[22:23]
	global_load_dword v165, v157, s[22:23] offset:64
	global_load_dword v168, v157, s[22:23] offset:128
	global_load_dword v169, v157, s[22:23] offset:192
	global_load_dword v170, v157, s[22:23] offset:512
	global_load_dword v171, v157, s[22:23] offset:576
	global_load_dword v161, v157, s[22:23] offset:640
	global_load_dword v160, v157, s[22:23] offset:704
	s_add_i32 s11, s20, s6
	v_bfe_u32 v181, v234, 2, 4
	v_or_b32_e32 v156, s11, v181
	v_and_b32_e32 v180, 3, v234
	v_and_b32_e32 v182, 0xffffffe7, v162
	v_lshl_or_b32 v182, v180, 3, v182
	v_mov_b32_e32 v183, 0
	v_lshl_or_b32 v180, v180, 4, v181
	v_lshlrev_b32_e32 v180, 2, v180
	s_waitcnt vmcnt(0)
	v_fmamk_f32 v157, v164, 0x3a800000, v236
	v_rsq_f32_e32 v164, v157
	v_ashrrev_i32_e32 v157, 31, v156
	v_lshlrev_b64 v[166:167], 13, v[156:157]
	v_pk_fma_f32 v[128:129], v[128:129], v[164:165], v[144:145] op_sel_hi:[1,0,1]
	v_pk_fma_f32 v[126:127], v[126:127], v[164:165], v[142:143] op_sel_hi:[1,0,1]
	v_pk_fma_f32 v[124:125], v[124:125], v[164:165], v[140:141] op_sel_hi:[1,0,1]
	v_pk_fma_f32 v[122:123], v[122:123], v[164:165], v[138:139] op_sel_hi:[1,0,1]
	v_max_f32_e32 v126, 0, v126
	v_max_f32_e32 v127, 0, v127
	v_max_f32_e32 v128, 0, v128
	v_max_f32_e32 v129, 0, v129
	v_max_f32_e32 v122, 0, v122
	v_max_f32_e32 v123, 0, v123
	v_max_f32_e32 v124, 0, v124
	v_max_f32_e32 v125, 0, v125
	v_pk_fma_f32 v[120:121], v[120:121], v[164:165], v[136:137] op_sel_hi:[1,0,1]
	v_pk_fma_f32 v[118:119], v[118:119], v[164:165], v[134:135] op_sel_hi:[1,0,1]
	v_pk_fma_f32 v[116:117], v[116:117], v[164:165], v[132:133] op_sel_hi:[1,0,1]
	v_pk_fma_f32 v[114:115], v[114:115], v[164:165], v[130:131] op_sel_hi:[1,0,1]
	v_pk_mul_f32 v[126:127], v[126:127], v[126:127]
	v_pk_mul_f32 v[128:129], v[128:129], v[128:129]
	v_pk_mul_f32 v[122:123], v[122:123], v[122:123]
	v_pk_mul_f32 v[124:125], v[124:125], v[124:125]
	v_max_f32_e32 v118, 0, v118
	v_max_f32_e32 v119, 0, v119
	v_max_f32_e32 v120, 0, v120
	v_max_f32_e32 v121, 0, v121
	v_max_f32_e32 v114, 0, v114
	v_max_f32_e32 v115, 0, v115
	v_max_f32_e32 v116, 0, v116
	v_max_f32_e32 v117, 0, v117
	v_cvt_pk_bf16_f32 v126, v126, v127
	v_cvt_pk_bf16_f32 v127, v128, v129
	v_cvt_pk_bf16_f32 v128, v122, v123
	v_cvt_pk_bf16_f32 v129, v124, v125
	v_lshl_add_u64 v[124:125], s[84:85], 0, v[166:167]
	v_lshlrev_b64 v[122:123], 1, v[182:183]
	v_pk_mul_f32 v[118:119], v[118:119], v[118:119]
	v_pk_mul_f32 v[120:121], v[120:121], v[120:121]
	v_pk_mul_f32 v[114:115], v[114:115], v[114:115]
	v_pk_mul_f32 v[116:117], v[116:117], v[116:117]
	v_lshl_add_u64 v[124:125], v[124:125], 0, v[122:123]
	v_cvt_pk_bf16_f32 v118, v118, v119
	v_cvt_pk_bf16_f32 v119, v120, v121
	v_cvt_pk_bf16_f32 v120, v114, v115
	v_cvt_pk_bf16_f32 v121, v116, v117
	ds_bpermute_b32 v126, v180, v126
	ds_bpermute_b32 v127, v180, v127
	ds_bpermute_b32 v128, v180, v128
	ds_bpermute_b32 v129, v180, v129
	ds_bpermute_b32 v118, v180, v118
	ds_bpermute_b32 v119, v180, v119
	ds_bpermute_b32 v120, v180, v120
	ds_bpermute_b32 v121, v180, v121
	v_fmamk_f32 v114, v165, 0x3a800000, v236
	v_rsq_f32_e32 v114, v114
	v_or_b32_e32 v116, 16, v156
	v_ashrrev_i32_e32 v117, 31, v116
	v_lshlrev_b64 v[116:117], 13, v[116:117]
	v_pk_fma_f32 v[112:113], v[112:113], v[114:115], v[144:145] op_sel_hi:[1,0,1]
	v_pk_fma_f32 v[110:111], v[110:111], v[114:115], v[142:143] op_sel_hi:[1,0,1]
	v_pk_fma_f32 v[106:107], v[106:107], v[114:115], v[138:139] op_sel_hi:[1,0,1]
	v_max_f32_e32 v110, 0, v110
	v_max_f32_e32 v111, 0, v111
	v_max_f32_e32 v112, 0, v112
	v_max_f32_e32 v113, 0, v113
	v_pk_fma_f32 v[108:109], v[108:109], v[114:115], v[140:141] op_sel_hi:[1,0,1]
	v_max_f32_e32 v106, 0, v106
	v_max_f32_e32 v107, 0, v107
	v_pk_fma_f32 v[104:105], v[104:105], v[114:115], v[136:137] op_sel_hi:[1,0,1]
	v_pk_fma_f32 v[102:103], v[102:103], v[114:115], v[134:135] op_sel_hi:[1,0,1]
	v_pk_fma_f32 v[100:101], v[100:101], v[114:115], v[132:133] op_sel_hi:[1,0,1]
	v_pk_fma_f32 v[98:99], v[98:99], v[114:115], v[130:131] op_sel_hi:[1,0,1]
	v_pk_mul_f32 v[110:111], v[110:111], v[110:111]
	v_pk_mul_f32 v[112:113], v[112:113], v[112:113]
	v_pk_mul_f32 v[106:107], v[106:107], v[106:107]
	v_max_f32_e32 v108, 0, v108
	v_max_f32_e32 v109, 0, v109
	v_max_f32_e32 v102, 0, v102
	v_max_f32_e32 v103, 0, v103
	v_max_f32_e32 v104, 0, v104
	v_max_f32_e32 v105, 0, v105
	v_max_f32_e32 v98, 0, v98
	v_max_f32_e32 v99, 0, v99
	v_max_f32_e32 v100, 0, v100
	v_max_f32_e32 v101, 0, v101
	v_cvt_pk_bf16_f32 v110, v110, v111
	v_cvt_pk_bf16_f32 v111, v112, v113
	v_pk_mul_f32 v[108:109], v[108:109], v[108:109]
	v_cvt_pk_bf16_f32 v112, v106, v107
	v_lshl_add_u64 v[106:107], s[84:85], 0, v[116:117]
	v_pk_mul_f32 v[102:103], v[102:103], v[102:103]
	v_pk_mul_f32 v[104:105], v[104:105], v[104:105]
	v_pk_mul_f32 v[98:99], v[98:99], v[98:99]
	v_pk_mul_f32 v[100:101], v[100:101], v[100:101]
	v_cvt_pk_bf16_f32 v113, v108, v109
	v_lshl_add_u64 v[106:107], v[106:107], 0, v[122:123]
	v_cvt_pk_bf16_f32 v102, v102, v103
	v_cvt_pk_bf16_f32 v103, v104, v105
	v_cvt_pk_bf16_f32 v104, v98, v99
	v_cvt_pk_bf16_f32 v105, v100, v101
	s_waitcnt lgkmcnt(0)
; template <int EPI>
; DI void gemm_epilogue(const Params& p, int layer, f32x4 (&acc)[2][2][4][2], int brow, int bcol, int pn, int wr, int wc,
;                       int fr, int fq, char* smem, int ksplit = -1) {
;     ...
; #pragma unroll
;     for (int ai = 0; ai < 2; ++ai)
; #pragma unroll
;       for (int m = 0; m < 4; ++m) {
;         __builtin_amdgcn_sched_barrier(0);
;         const int row = brow + ai * 128 + wr * 64 + m * 16 + fr;
;         const float rs = __builtin_amdgcn_rsqf(rsv[ai][m] * (1.f / DM) + EPSN);
; #pragma unroll
;         for (int bj = 0; bj < 2; ++bj) {
;           u32x4 o;
; #pragma unroll
;           for (int n = 0; n < 2; ++n) {
;             f32x4 v = acc[ai][bj][m][n] * rs + bv[bj][n];
; #pragma unroll
;             for (int j = 0; j < 4; ++j) {
;               float r = fmaxf(v[j], 0.f);
;               v[j] = r * r;
;             }
;             o[2 * n] = pk_bf16(v[0], v[1]);
;             o[2 * n + 1] = pk_bf16(v[2], v[3]);
;           }
;           *(u32x4*)(p.hid + (size_t)row * HID + colb + bj * 128) = o;
;         }
;       }
	global_store_dwordx4 v[124:125], v[126:129], off
	global_store_dwordx4 v[124:125], v[118:121], off offset:256
	ds_bpermute_b32 v110, v180, v110
	ds_bpermute_b32 v111, v180, v111
	ds_bpermute_b32 v112, v180, v112
	ds_bpermute_b32 v113, v180, v113
	ds_bpermute_b32 v102, v180, v102
	ds_bpermute_b32 v103, v180, v103
	ds_bpermute_b32 v104, v180, v104
	ds_bpermute_b32 v105, v180, v105
	v_fmamk_f32 v98, v168, 0x3a800000, v236
	v_rsq_f32_e32 v98, v98
	v_or_b32_e32 v100, 32, v156
	v_ashrrev_i32_e32 v101, 31, v100
	v_lshlrev_b64 v[100:101], 13, v[100:101]
	v_pk_fma_f32 v[96:97], v[96:97], v[98:99], v[144:145] op_sel_hi:[1,0,1]
	v_pk_fma_f32 v[94:95], v[94:95], v[98:99], v[142:143] op_sel_hi:[1,0,1]
	v_pk_fma_f32 v[90:91], v[90:91], v[98:99], v[138:139] op_sel_hi:[1,0,1]
	v_max_f32_e32 v94, 0, v94
	v_max_f32_e32 v95, 0, v95
	v_max_f32_e32 v96, 0, v96
	v_max_f32_e32 v97, 0, v97
	v_pk_fma_f32 v[92:93], v[92:93], v[98:99], v[140:141] op_sel_hi:[1,0,1]
	v_max_f32_e32 v90, 0, v90
	v_max_f32_e32 v91, 0, v91
	v_pk_fma_f32 v[88:89], v[88:89], v[98:99], v[136:137] op_sel_hi:[1,0,1]
	v_pk_fma_f32 v[86:87], v[86:87], v[98:99], v[134:135] op_sel_hi:[1,0,1]
	v_pk_fma_f32 v[84:85], v[84:85], v[98:99], v[132:133] op_sel_hi:[1,0,1]
	v_pk_fma_f32 v[82:83], v[82:83], v[98:99], v[130:131] op_sel_hi:[1,0,1]
	v_pk_mul_f32 v[94:95], v[94:95], v[94:95]
	v_pk_mul_f32 v[96:97], v[96:97], v[96:97]
	v_pk_mul_f32 v[90:91], v[90:91], v[90:91]
	v_max_f32_e32 v92, 0, v92
	v_max_f32_e32 v93, 0, v93
	v_max_f32_e32 v86, 0, v86
	v_max_f32_e32 v87, 0, v87
	v_max_f32_e32 v88, 0, v88
	v_max_f32_e32 v89, 0, v89
	v_max_f32_e32 v82, 0, v82
	v_max_f32_e32 v83, 0, v83
	v_max_f32_e32 v84, 0, v84
	v_max_f32_e32 v85, 0, v85
	v_cvt_pk_bf16_f32 v94, v94, v95
	v_cvt_pk_bf16_f32 v95, v96, v97
	v_pk_mul_f32 v[92:93], v[92:93], v[92:93]
	v_cvt_pk_bf16_f32 v96, v90, v91
	v_lshl_add_u64 v[90:91], s[84:85], 0, v[100:101]
	v_pk_mul_f32 v[86:87], v[86:87], v[86:87]
	v_pk_mul_f32 v[88:89], v[88:89], v[88:89]
	v_pk_mul_f32 v[82:83], v[82:83], v[82:83]
	v_pk_mul_f32 v[84:85], v[84:85], v[84:85]
	v_cvt_pk_bf16_f32 v97, v92, v93
	v_lshl_add_u64 v[90:91], v[90:91], 0, v[122:123]
	v_cvt_pk_bf16_f32 v86, v86, v87
	v_cvt_pk_bf16_f32 v87, v88, v89
	v_cvt_pk_bf16_f32 v88, v82, v83
	v_cvt_pk_bf16_f32 v89, v84, v85
	s_waitcnt lgkmcnt(0)
	global_store_dwordx4 v[106:107], v[110:113], off
	global_store_dwordx4 v[106:107], v[102:105], off offset:256
	ds_bpermute_b32 v94, v180, v94
	ds_bpermute_b32 v95, v180, v95
	ds_bpermute_b32 v96, v180, v96
	ds_bpermute_b32 v97, v180, v97
	ds_bpermute_b32 v86, v180, v86
	ds_bpermute_b32 v87, v180, v87
	ds_bpermute_b32 v88, v180, v88
	ds_bpermute_b32 v89, v180, v89
	v_fmamk_f32 v82, v169, 0x3a800000, v236
	v_rsq_f32_e32 v82, v82
	v_or_b32_e32 v84, 48, v156
	v_ashrrev_i32_e32 v85, 31, v84
	v_lshlrev_b64 v[84:85], 13, v[84:85]
	v_pk_fma_f32 v[80:81], v[80:81], v[82:83], v[144:145] op_sel_hi:[1,0,1]
	v_pk_fma_f32 v[78:79], v[78:79], v[82:83], v[142:143] op_sel_hi:[1,0,1]
	v_pk_fma_f32 v[74:75], v[74:75], v[82:83], v[138:139] op_sel_hi:[1,0,1]
	v_max_f32_e32 v78, 0, v78
	v_max_f32_e32 v79, 0, v79
	v_max_f32_e32 v80, 0, v80
	v_max_f32_e32 v81, 0, v81
	v_pk_fma_f32 v[76:77], v[76:77], v[82:83], v[140:141] op_sel_hi:[1,0,1]
	v_max_f32_e32 v74, 0, v74
	v_max_f32_e32 v75, 0, v75
	v_pk_fma_f32 v[72:73], v[72:73], v[82:83], v[136:137] op_sel_hi:[1,0,1]
	v_pk_fma_f32 v[70:71], v[70:71], v[82:83], v[134:135] op_sel_hi:[1,0,1]
	v_pk_fma_f32 v[68:69], v[68:69], v[82:83], v[132:133] op_sel_hi:[1,0,1]
	v_pk_fma_f32 v[66:67], v[66:67], v[82:83], v[130:131] op_sel_hi:[1,0,1]
	v_pk_mul_f32 v[78:79], v[78:79], v[78:79]
	v_pk_mul_f32 v[80:81], v[80:81], v[80:81]
	v_pk_mul_f32 v[74:75], v[74:75], v[74:75]
	v_max_f32_e32 v76, 0, v76
	v_max_f32_e32 v77, 0, v77
	v_max_f32_e32 v70, 0, v70
	v_max_f32_e32 v71, 0, v71
	v_max_f32_e32 v72, 0, v72
	v_max_f32_e32 v73, 0, v73
	v_max_f32_e32 v66, 0, v66
	v_max_f32_e32 v67, 0, v67
	v_max_f32_e32 v68, 0, v68
	v_max_f32_e32 v69, 0, v69
	v_cvt_pk_bf16_f32 v78, v78, v79
	v_cvt_pk_bf16_f32 v79, v80, v81
	v_pk_mul_f32 v[76:77], v[76:77], v[76:77]
	v_cvt_pk_bf16_f32 v80, v74, v75
	v_lshl_add_u64 v[74:75], s[84:85], 0, v[84:85]
	v_pk_mul_f32 v[70:71], v[70:71], v[70:71]
	v_pk_mul_f32 v[72:73], v[72:73], v[72:73]
	v_pk_mul_f32 v[66:67], v[66:67], v[66:67]
	v_pk_mul_f32 v[68:69], v[68:69], v[68:69]
	v_cvt_pk_bf16_f32 v81, v76, v77
	v_lshl_add_u64 v[74:75], v[74:75], 0, v[122:123]
	v_cvt_pk_bf16_f32 v70, v70, v71
	v_cvt_pk_bf16_f32 v71, v72, v73
	v_cvt_pk_bf16_f32 v72, v66, v67
	v_cvt_pk_bf16_f32 v73, v68, v69
	s_waitcnt lgkmcnt(0)
; template <int EPI>
; DI void gemm_epilogue(const Params& p, int layer, f32x4 (&acc)[2][2][4][2], int brow, int bcol, int pn, int wr, int wc,
;                       int fr, int fq, char* smem, int ksplit = -1) {
;     ...
; #pragma unroll
;     for (int ai = 0; ai < 2; ++ai)
; #pragma unroll
;       for (int m = 0; m < 4; ++m) {
;         __builtin_amdgcn_sched_barrier(0);
;         const int row = brow + ai * 128 + wr * 64 + m * 16 + fr;
;         const float rs = __builtin_amdgcn_rsqf(rsv[ai][m] * (1.f / DM) + EPSN);
; #pragma unroll
;         for (int bj = 0; bj < 2; ++bj) {
;           u32x4 o;
; #pragma unroll
;           for (int n = 0; n < 2; ++n) {
;             f32x4 v = acc[ai][bj][m][n] * rs + bv[bj][n];
; #pragma unroll
;             for (int j = 0; j < 4; ++j) {
;               float r = fmaxf(v[j], 0.f);
;               v[j] = r * r;
;             }
;             o[2 * n] = pk_bf16(v[0], v[1]);
;             o[2 * n + 1] = pk_bf16(v[2], v[3]);
;           }
;           *(u32x4*)(p.hid + (size_t)row * HID + colb + bj * 128) = o;
;         }
;       }
	global_store_dwordx4 v[90:91], v[94:97], off
	global_store_dwordx4 v[90:91], v[86:89], off offset:256
	ds_bpermute_b32 v78, v180, v78
	ds_bpermute_b32 v79, v180, v79
	ds_bpermute_b32 v80, v180, v80
	ds_bpermute_b32 v81, v180, v81
	ds_bpermute_b32 v70, v180, v70
	ds_bpermute_b32 v71, v180, v71
	ds_bpermute_b32 v72, v180, v72
	ds_bpermute_b32 v73, v180, v73
	v_add_u32_e32 v66, 0x80, v156
	v_fmamk_f32 v67, v170, 0x3a800000, v236
	v_rsq_f32_e32 v68, v67
	v_ashrrev_i32_e32 v67, 31, v66
	v_lshlrev_b64 v[66:67], 13, v[66:67]
	v_pk_fma_f32 v[64:65], v[64:65], v[68:69], v[144:145] op_sel_hi:[1,0,1]
	v_pk_fma_f32 v[62:63], v[62:63], v[68:69], v[142:143] op_sel_hi:[1,0,1]
	v_pk_fma_f32 v[58:59], v[58:59], v[68:69], v[138:139] op_sel_hi:[1,0,1]
	v_max_f32_e32 v62, 0, v62
	v_max_f32_e32 v63, 0, v63
	v_max_f32_e32 v64, 0, v64
	v_max_f32_e32 v65, 0, v65
	v_pk_fma_f32 v[60:61], v[60:61], v[68:69], v[140:141] op_sel_hi:[1,0,1]
	v_max_f32_e32 v58, 0, v58
	v_max_f32_e32 v59, 0, v59
	v_pk_fma_f32 v[56:57], v[56:57], v[68:69], v[136:137] op_sel_hi:[1,0,1]
	v_pk_fma_f32 v[54:55], v[54:55], v[68:69], v[134:135] op_sel_hi:[1,0,1]
	v_pk_fma_f32 v[52:53], v[52:53], v[68:69], v[132:133] op_sel_hi:[1,0,1]
	v_pk_fma_f32 v[50:51], v[50:51], v[68:69], v[130:131] op_sel_hi:[1,0,1]
	v_pk_mul_f32 v[62:63], v[62:63], v[62:63]
	v_pk_mul_f32 v[64:65], v[64:65], v[64:65]
	v_pk_mul_f32 v[58:59], v[58:59], v[58:59]
	v_max_f32_e32 v60, 0, v60
	v_max_f32_e32 v61, 0, v61
	v_max_f32_e32 v54, 0, v54
	v_max_f32_e32 v55, 0, v55
	v_max_f32_e32 v56, 0, v56
	v_max_f32_e32 v57, 0, v57
	v_max_f32_e32 v50, 0, v50
	v_max_f32_e32 v51, 0, v51
	v_max_f32_e32 v52, 0, v52
	v_max_f32_e32 v53, 0, v53
	v_cvt_pk_bf16_f32 v62, v62, v63
	v_cvt_pk_bf16_f32 v63, v64, v65
	v_pk_mul_f32 v[60:61], v[60:61], v[60:61]
	v_cvt_pk_bf16_f32 v64, v58, v59
	v_lshl_add_u64 v[58:59], s[84:85], 0, v[66:67]
	v_pk_mul_f32 v[54:55], v[54:55], v[54:55]
	v_pk_mul_f32 v[56:57], v[56:57], v[56:57]
	v_pk_mul_f32 v[50:51], v[50:51], v[50:51]
	v_pk_mul_f32 v[52:53], v[52:53], v[52:53]
	v_cvt_pk_bf16_f32 v65, v60, v61
	v_lshl_add_u64 v[58:59], v[58:59], 0, v[122:123]
	v_cvt_pk_bf16_f32 v54, v54, v55
	v_cvt_pk_bf16_f32 v55, v56, v57
	v_cvt_pk_bf16_f32 v56, v50, v51
	v_cvt_pk_bf16_f32 v57, v52, v53
	s_waitcnt lgkmcnt(0)
	global_store_dwordx4 v[74:75], v[78:81], off
	global_store_dwordx4 v[74:75], v[70:73], off offset:256
	ds_bpermute_b32 v62, v180, v62
	ds_bpermute_b32 v63, v180, v63
	ds_bpermute_b32 v64, v180, v64
	ds_bpermute_b32 v65, v180, v65
	ds_bpermute_b32 v54, v180, v54
	ds_bpermute_b32 v55, v180, v55
	ds_bpermute_b32 v56, v180, v56
	ds_bpermute_b32 v57, v180, v57
	v_fmamk_f32 v50, v171, 0x3a800000, v236
	v_rsq_f32_e32 v50, v50
	v_add_u32_e32 v52, 0x90, v156
	v_ashrrev_i32_e32 v53, 31, v52
	v_lshlrev_b64 v[52:53], 13, v[52:53]
	v_pk_fma_f32 v[48:49], v[48:49], v[50:51], v[144:145] op_sel_hi:[1,0,1]
	v_pk_fma_f32 v[46:47], v[46:47], v[50:51], v[142:143] op_sel_hi:[1,0,1]
	v_pk_fma_f32 v[42:43], v[42:43], v[50:51], v[138:139] op_sel_hi:[1,0,1]
	v_max_f32_e32 v46, 0, v46
	v_max_f32_e32 v47, 0, v47
	v_max_f32_e32 v48, 0, v48
	v_max_f32_e32 v49, 0, v49
	v_pk_fma_f32 v[44:45], v[44:45], v[50:51], v[140:141] op_sel_hi:[1,0,1]
	v_max_f32_e32 v42, 0, v42
	v_max_f32_e32 v43, 0, v43
	v_pk_fma_f32 v[40:41], v[40:41], v[50:51], v[136:137] op_sel_hi:[1,0,1]
	v_pk_fma_f32 v[38:39], v[38:39], v[50:51], v[134:135] op_sel_hi:[1,0,1]
	v_pk_fma_f32 v[36:37], v[36:37], v[50:51], v[132:133] op_sel_hi:[1,0,1]
	v_pk_fma_f32 v[34:35], v[34:35], v[50:51], v[130:131] op_sel_hi:[1,0,1]
	v_pk_mul_f32 v[46:47], v[46:47], v[46:47]
	v_pk_mul_f32 v[48:49], v[48:49], v[48:49]
	v_pk_mul_f32 v[42:43], v[42:43], v[42:43]
	v_max_f32_e32 v44, 0, v44
	v_max_f32_e32 v45, 0, v45
	v_max_f32_e32 v38, 0, v38
	v_max_f32_e32 v39, 0, v39
	v_max_f32_e32 v40, 0, v40
	v_max_f32_e32 v41, 0, v41
	v_max_f32_e32 v34, 0, v34
	v_max_f32_e32 v35, 0, v35
	v_max_f32_e32 v36, 0, v36
	v_max_f32_e32 v37, 0, v37
	v_cvt_pk_bf16_f32 v46, v46, v47
	v_cvt_pk_bf16_f32 v47, v48, v49
	v_pk_mul_f32 v[44:45], v[44:45], v[44:45]
	v_cvt_pk_bf16_f32 v48, v42, v43
	v_lshl_add_u64 v[42:43], s[84:85], 0, v[52:53]
	v_pk_mul_f32 v[38:39], v[38:39], v[38:39]
	v_pk_mul_f32 v[40:41], v[40:41], v[40:41]
	v_pk_mul_f32 v[34:35], v[34:35], v[34:35]
	v_pk_mul_f32 v[36:37], v[36:37], v[36:37]
	v_cvt_pk_bf16_f32 v49, v44, v45
	v_lshl_add_u64 v[42:43], v[42:43], 0, v[122:123]
	v_cvt_pk_bf16_f32 v38, v38, v39
	v_cvt_pk_bf16_f32 v39, v40, v41
	v_cvt_pk_bf16_f32 v40, v34, v35
	v_cvt_pk_bf16_f32 v41, v36, v37
	s_waitcnt lgkmcnt(0)
; template <int EPI>
; DI void gemm_epilogue(const Params& p, int layer, f32x4 (&acc)[2][2][4][2], int brow, int bcol, int pn, int wr, int wc,
;                       int fr, int fq, char* smem, int ksplit = -1) {
;     ...
; #pragma unroll
;     for (int ai = 0; ai < 2; ++ai)
; #pragma unroll
;       for (int m = 0; m < 4; ++m) {
;         __builtin_amdgcn_sched_barrier(0);
;         const int row = brow + ai * 128 + wr * 64 + m * 16 + fr;
;         const float rs = __builtin_amdgcn_rsqf(rsv[ai][m] * (1.f / DM) + EPSN);
; #pragma unroll
;         for (int bj = 0; bj < 2; ++bj) {
;           u32x4 o;
; #pragma unroll
;           for (int n = 0; n < 2; ++n) {
;             f32x4 v = acc[ai][bj][m][n] * rs + bv[bj][n];
; #pragma unroll
;             for (int j = 0; j < 4; ++j) {
;               float r = fmaxf(v[j], 0.f);
;               v[j] = r * r;
;             }
;             o[2 * n] = pk_bf16(v[0], v[1]);
;             o[2 * n + 1] = pk_bf16(v[2], v[3]);
;           }
;           *(u32x4*)(p.hid + (size_t)row * HID + colb + bj * 128) = o;
;         }
;       }
	global_store_dwordx4 v[58:59], v[62:65], off
	global_store_dwordx4 v[58:59], v[54:57], off offset:256
	ds_bpermute_b32 v46, v180, v46
	ds_bpermute_b32 v47, v180, v47
	ds_bpermute_b32 v48, v180, v48
	ds_bpermute_b32 v49, v180, v49
	ds_bpermute_b32 v38, v180, v38
	ds_bpermute_b32 v39, v180, v39
	ds_bpermute_b32 v40, v180, v40
	ds_bpermute_b32 v41, v180, v41
	v_fmamk_f32 v34, v161, 0x3a800000, v236
	v_rsq_f32_e32 v34, v34
	v_add_u32_e32 v36, 0xa0, v156
	v_ashrrev_i32_e32 v37, 31, v36
	v_lshlrev_b64 v[36:37], 13, v[36:37]
	v_pk_fma_f32 v[32:33], v[32:33], v[34:35], v[144:145] op_sel_hi:[1,0,1]
	v_pk_fma_f32 v[30:31], v[30:31], v[34:35], v[142:143] op_sel_hi:[1,0,1]
	v_pk_fma_f32 v[26:27], v[26:27], v[34:35], v[138:139] op_sel_hi:[1,0,1]
	v_max_f32_e32 v30, 0, v30
	v_max_f32_e32 v31, 0, v31
	v_max_f32_e32 v32, 0, v32
	v_max_f32_e32 v33, 0, v33
	v_pk_fma_f32 v[28:29], v[28:29], v[34:35], v[140:141] op_sel_hi:[1,0,1]
	v_max_f32_e32 v26, 0, v26
	v_max_f32_e32 v27, 0, v27
	v_pk_fma_f32 v[24:25], v[24:25], v[34:35], v[136:137] op_sel_hi:[1,0,1]
	v_pk_fma_f32 v[22:23], v[22:23], v[34:35], v[134:135] op_sel_hi:[1,0,1]
	v_pk_fma_f32 v[20:21], v[20:21], v[34:35], v[132:133] op_sel_hi:[1,0,1]
	v_pk_fma_f32 v[18:19], v[18:19], v[34:35], v[130:131] op_sel_hi:[1,0,1]
	v_pk_mul_f32 v[30:31], v[30:31], v[30:31]
	v_pk_mul_f32 v[32:33], v[32:33], v[32:33]
	v_pk_mul_f32 v[26:27], v[26:27], v[26:27]
	v_max_f32_e32 v28, 0, v28
	v_max_f32_e32 v29, 0, v29
	v_max_f32_e32 v22, 0, v22
	v_max_f32_e32 v23, 0, v23
	v_max_f32_e32 v24, 0, v24
	v_max_f32_e32 v25, 0, v25
	v_max_f32_e32 v18, 0, v18
	v_max_f32_e32 v19, 0, v19
	v_max_f32_e32 v20, 0, v20
	v_max_f32_e32 v21, 0, v21
	v_cvt_pk_bf16_f32 v30, v30, v31
	v_cvt_pk_bf16_f32 v31, v32, v33
	v_pk_mul_f32 v[28:29], v[28:29], v[28:29]
	v_cvt_pk_bf16_f32 v32, v26, v27
	v_lshl_add_u64 v[26:27], s[84:85], 0, v[36:37]
	v_pk_mul_f32 v[22:23], v[22:23], v[22:23]
	v_pk_mul_f32 v[24:25], v[24:25], v[24:25]
	v_pk_mul_f32 v[18:19], v[18:19], v[18:19]
	v_pk_mul_f32 v[20:21], v[20:21], v[20:21]
	v_cvt_pk_bf16_f32 v33, v28, v29
	v_lshl_add_u64 v[26:27], v[26:27], 0, v[122:123]
	v_cvt_pk_bf16_f32 v22, v22, v23
	v_cvt_pk_bf16_f32 v23, v24, v25
	v_cvt_pk_bf16_f32 v24, v18, v19
	v_cvt_pk_bf16_f32 v25, v20, v21
	s_waitcnt lgkmcnt(0)
	global_store_dwordx4 v[42:43], v[46:49], off
	global_store_dwordx4 v[42:43], v[38:41], off offset:256
	ds_bpermute_b32 v30, v180, v30
	ds_bpermute_b32 v31, v180, v31
	ds_bpermute_b32 v32, v180, v32
	ds_bpermute_b32 v33, v180, v33
	ds_bpermute_b32 v22, v180, v22
	ds_bpermute_b32 v23, v180, v23
	ds_bpermute_b32 v24, v180, v24
	ds_bpermute_b32 v25, v180, v25
	v_fmamk_f32 v18, v160, 0x3a800000, v236
	v_rsq_f32_e32 v18, v18
	v_add_u32_e32 v20, 0xb0, v156
	v_ashrrev_i32_e32 v21, 31, v20
	v_lshlrev_b64 v[20:21], 13, v[20:21]
	v_pk_fma_f32 v[16:17], v[16:17], v[18:19], v[144:145] op_sel_hi:[1,0,1]
	v_pk_fma_f32 v[14:15], v[14:15], v[18:19], v[142:143] op_sel_hi:[1,0,1]
	v_pk_fma_f32 v[10:11], v[10:11], v[18:19], v[138:139] op_sel_hi:[1,0,1]
	v_max_f32_e32 v14, 0, v14
	v_max_f32_e32 v15, 0, v15
	v_max_f32_e32 v16, 0, v16
	v_max_f32_e32 v17, 0, v17
	v_pk_fma_f32 v[12:13], v[12:13], v[18:19], v[140:141] op_sel_hi:[1,0,1]
	v_max_f32_e32 v10, 0, v10
	v_max_f32_e32 v11, 0, v11
	v_pk_fma_f32 v[8:9], v[8:9], v[18:19], v[136:137] op_sel_hi:[1,0,1]
	v_pk_fma_f32 v[6:7], v[6:7], v[18:19], v[134:135] op_sel_hi:[1,0,1]
	v_pk_fma_f32 v[4:5], v[4:5], v[18:19], v[132:133] op_sel_hi:[1,0,1]
	v_pk_fma_f32 v[2:3], v[2:3], v[18:19], v[130:131] op_sel_hi:[1,0,1]
	v_pk_mul_f32 v[14:15], v[14:15], v[14:15]
	v_pk_mul_f32 v[16:17], v[16:17], v[16:17]
	v_pk_mul_f32 v[10:11], v[10:11], v[10:11]
	v_max_f32_e32 v12, 0, v12
	v_max_f32_e32 v13, 0, v13
	v_max_f32_e32 v6, 0, v6
	v_max_f32_e32 v7, 0, v7
	v_max_f32_e32 v8, 0, v8
	v_max_f32_e32 v9, 0, v9
	v_max_f32_e32 v2, 0, v2
	v_max_f32_e32 v3, 0, v3
	v_max_f32_e32 v4, 0, v4
	v_max_f32_e32 v5, 0, v5
	v_cvt_pk_bf16_f32 v14, v14, v15
	v_cvt_pk_bf16_f32 v15, v16, v17
	v_pk_mul_f32 v[12:13], v[12:13], v[12:13]
	v_cvt_pk_bf16_f32 v16, v10, v11
	v_lshl_add_u64 v[10:11], s[84:85], 0, v[20:21]
	v_pk_mul_f32 v[6:7], v[6:7], v[6:7]
	v_pk_mul_f32 v[8:9], v[8:9], v[8:9]
	v_pk_mul_f32 v[2:3], v[2:3], v[2:3]
	v_pk_mul_f32 v[4:5], v[4:5], v[4:5]
	v_cvt_pk_bf16_f32 v17, v12, v13
	v_lshl_add_u64 v[10:11], v[10:11], 0, v[122:123]
	v_cvt_pk_bf16_f32 v6, v6, v7
	v_cvt_pk_bf16_f32 v7, v8, v9
	v_cvt_pk_bf16_f32 v8, v2, v3
	v_cvt_pk_bf16_f32 v9, v4, v5
	s_andn2_b64 vcc, exec, s[0:1]
	s_mov_b64 s[0:1], -1
	s_waitcnt lgkmcnt(0)
	global_store_dwordx4 v[26:27], v[30:33], off
	global_store_dwordx4 v[26:27], v[22:25], off offset:256
	ds_bpermute_b32 v14, v180, v14
	ds_bpermute_b32 v15, v180, v15
	ds_bpermute_b32 v16, v180, v16
	ds_bpermute_b32 v17, v180, v17
	ds_bpermute_b32 v6, v180, v6
	ds_bpermute_b32 v7, v180, v7
	ds_bpermute_b32 v8, v180, v8
	ds_bpermute_b32 v9, v180, v9
	s_waitcnt lgkmcnt(0)
	global_store_dwordx4 v[10:11], v[14:17], off
	global_store_dwordx4 v[10:11], v[6:9], off offset:256
	s_cbranch_vccnz .LBB0_990
	s_andn2_b64 vcc, exec, s[4:5]
	s_cbranch_vccnz .LBB0_989
	s_barrier
	s_branch .LBB0_989
